# hand-written qkprep row loop (dword accesses, head-pair lanes, all rows loaded up front, DPP reductions)
# baseline (speedup 1.0000x reference)
.LBB0_739:
	s_mov_b64 s[40:41], s[88:89]
	s_load_dwordx4 s[52:55], s[40:41], 0xb0
	s_load_dwordx4 s[48:51], s[40:41], 0x10
	s_waitcnt vmcnt(0)
	v_mov_b32_e32 v2, v204
	v_readlane_b32 s3, v254, 2
	s_waitcnt lgkmcnt(0)
	s_add_u32 s64, s54, 0x12dc8000
	s_addc_u32 s65, s55, 0
	v_ashrrev_i32_e32 v1, 6, v2
	s_waitcnt vmcnt(8)
	v_and_b32_e32 v4, 63, v2
	s_add_u32 s66, s54, 0x13208000
	v_add_u32_e32 v1, s3, v1
	s_movk_i32 s3, 0x3000
	s_addc_u32 s67, s55, 0
	v_lshlrev_b32_e32 v0, 1, v4
	v_cmp_gt_i32_e32 vcc, s3, v1
	s_and_saveexec_b64 s[68:69], vcc
	s_cbranch_execz .LBB0_766
	s_load_dwordx4 s[44:47], s[88:89], 0x80
	v_readfirstlane_b32 s70, v1
	v_and_b32_e32 v2, 15, v205
	v_bfe_u32 v3, v205, 4, 1
	v_lshrrev_b32_e32 v16, 5, v205
	v_lshlrev_b32_e32 v17, 2, v2
	v_lshl_add_u32 v17, v3, 7, v17
	v_lshl_add_u32 v18, v16, 8, v17
	v_mul_u32_u24_e32 v19, 0x110000, v16
	v_add_u32_e32 v19, v19, v17
	v_lshl_add_u32 v20, v16, 16, v17
	v_lshlrev_b32_e32 v24, 3, v2
	v_lshl_add_u32 v24, v3, 8, v24
	v_lshl_add_u32 v21, v16, 17, v24
	v_lshlrev_b32_e32 v22, 2, v205
	v_lshlrev_b32_e32 v23, 3, v205
	v_lshlrev_b32_e32 v25, 2, v2
	v_cvt_f32_ubyte0_e32 v26, v25
	v_add_u32_e32 v25, 2, v25
	v_cvt_f32_ubyte0_e32 v27, v25
	v_mul_f32_e32 v26, 0xbe549a78, v26
	v_mul_f32_e32 v27, 0xbe549a78, v27
	v_exp_f32_e32 v26, v26
	v_exp_f32_e32 v27, v27
	v_cmp_eq_u32_e64 s[42:43], 0, v3
	s_waitcnt lgkmcnt(0)
	global_load_dwordx2 v[4:5], v24, s[44:45]
	global_load_dwordx2 v[6:7], v24, s[44:45] offset:128
	global_load_dwordx2 v[8:9], v24, s[46:47]
	global_load_dwordx2 v[10:11], v24, s[46:47] offset:128
	s_add_i32 s71, s70, 0x0
	s_mul_i32 s71, s71, 0xc00
	s_add_u32 s71, s71, 0xb7c8000
	s_add_u32 s4, s54, s71
	s_addc_u32 s5, s55, 0
	global_load_dword v100, v18, s[4:5] offset:0
	global_load_dword v101, v18, s[4:5] offset:64
	global_load_dword v102, v18, s[4:5] offset:512
	global_load_dword v103, v18, s[4:5] offset:576
	global_load_dword v104, v18, s[4:5] offset:1024
	global_load_dword v105, v18, s[4:5] offset:1088
	global_load_dword v106, v18, s[4:5] offset:1536
	global_load_dword v107, v18, s[4:5] offset:1600
	global_load_dword v108, v18, s[4:5] offset:2048
	global_load_dword v109, v18, s[4:5] offset:2112
	global_load_dword v110, v22, s[4:5] offset:2560
	global_load_dword v111, v22, s[4:5] offset:2816
	s_add_i32 s71, s70, 0x800
	s_mul_i32 s71, s71, 0xc00
	s_add_u32 s71, s71, 0xb7c8000
	s_add_u32 s4, s54, s71
	s_addc_u32 s5, s55, 0
	global_load_dword v112, v18, s[4:5] offset:0
	global_load_dword v113, v18, s[4:5] offset:64
	global_load_dword v114, v18, s[4:5] offset:512
	global_load_dword v115, v18, s[4:5] offset:576
	global_load_dword v116, v18, s[4:5] offset:1024
	global_load_dword v117, v18, s[4:5] offset:1088
	global_load_dword v118, v18, s[4:5] offset:1536
	global_load_dword v119, v18, s[4:5] offset:1600
	global_load_dword v120, v18, s[4:5] offset:2048
	global_load_dword v121, v18, s[4:5] offset:2112
	global_load_dword v122, v22, s[4:5] offset:2560
	global_load_dword v123, v22, s[4:5] offset:2816
	s_add_i32 s71, s70, 0x1000
	s_mul_i32 s71, s71, 0xc00
	s_add_u32 s71, s71, 0xb7c8000
	s_add_u32 s4, s54, s71
	s_addc_u32 s5, s55, 0
	global_load_dword v124, v18, s[4:5] offset:0
	global_load_dword v125, v18, s[4:5] offset:64
	global_load_dword v126, v18, s[4:5] offset:512
	global_load_dword v127, v18, s[4:5] offset:576
	global_load_dword v128, v18, s[4:5] offset:1024
	global_load_dword v129, v18, s[4:5] offset:1088
	global_load_dword v130, v18, s[4:5] offset:1536
	global_load_dword v131, v18, s[4:5] offset:1600
	global_load_dword v132, v18, s[4:5] offset:2048
	global_load_dword v133, v18, s[4:5] offset:2112
	global_load_dword v134, v22, s[4:5] offset:2560
	global_load_dword v135, v22, s[4:5] offset:2816
	s_add_i32 s71, s70, 0x1800
	s_mul_i32 s71, s71, 0xc00
	s_add_u32 s71, s71, 0xb7c8000
	s_add_u32 s4, s54, s71
	s_addc_u32 s5, s55, 0
	global_load_dword v136, v18, s[4:5] offset:0
	global_load_dword v137, v18, s[4:5] offset:64
	global_load_dword v138, v18, s[4:5] offset:512
	global_load_dword v139, v18, s[4:5] offset:576
	global_load_dword v140, v18, s[4:5] offset:1024
	global_load_dword v141, v18, s[4:5] offset:1088
	global_load_dword v142, v18, s[4:5] offset:1536
	global_load_dword v143, v18, s[4:5] offset:1600
	global_load_dword v144, v18, s[4:5] offset:2048
	global_load_dword v145, v18, s[4:5] offset:2112
	global_load_dword v146, v22, s[4:5] offset:2560
	global_load_dword v147, v22, s[4:5] offset:2816
	s_add_i32 s71, s70, 0x2000
	s_mul_i32 s71, s71, 0xc00
	s_add_u32 s71, s71, 0xb7c8000
	s_add_u32 s4, s54, s71
	s_addc_u32 s5, s55, 0
	global_load_dword v148, v18, s[4:5] offset:0
	global_load_dword v149, v18, s[4:5] offset:64
	global_load_dword v150, v18, s[4:5] offset:512
	global_load_dword v151, v18, s[4:5] offset:576
	global_load_dword v152, v18, s[4:5] offset:1024
	global_load_dword v153, v18, s[4:5] offset:1088
	global_load_dword v154, v18, s[4:5] offset:1536
	global_load_dword v155, v18, s[4:5] offset:1600
	global_load_dword v156, v18, s[4:5] offset:2048
	global_load_dword v157, v18, s[4:5] offset:2112
	global_load_dword v158, v22, s[4:5] offset:2560
	global_load_dword v159, v22, s[4:5] offset:2816
	s_add_i32 s71, s70, 0x2800
	s_mul_i32 s71, s71, 0xc00
	s_add_u32 s71, s71, 0xb7c8000
	s_add_u32 s4, s54, s71
	s_addc_u32 s5, s55, 0
	global_load_dword v160, v18, s[4:5] offset:0
	global_load_dword v161, v18, s[4:5] offset:64
	global_load_dword v162, v18, s[4:5] offset:512
	global_load_dword v163, v18, s[4:5] offset:576
	global_load_dword v164, v18, s[4:5] offset:1024
	global_load_dword v165, v18, s[4:5] offset:1088
	global_load_dword v166, v18, s[4:5] offset:1536
	global_load_dword v167, v18, s[4:5] offset:1600
	global_load_dword v168, v18, s[4:5] offset:2048
	global_load_dword v169, v18, s[4:5] offset:2112
	global_load_dword v170, v22, s[4:5] offset:2560
	global_load_dword v171, v22, s[4:5] offset:2816
	s_add_i32 s71, s70, 0x0
	s_lshr_b32 s11, s71, 8
	s_and_b32 s10, s71, 0xff
	s_lshl_b32 s11, s11, 9
	s_add_i32 s10, s10, s11
	s_lshl_b32 s74, s71, 11
	s_add_u32 s74, s74, 0x87c8000
	s_add_u32 s74, s54, s74
	s_addc_u32 s75, s55, 0
	s_lshl_b32 s76, s10, 8
	s_add_u32 s78, s76, 0x12bc8000
	s_add_u32 s76, s76, 0x129c8000
	s_add_u32 s76, s54, s76
	s_addc_u32 s77, s55, 0
	s_add_u32 s78, s54, s78
	s_addc_u32 s79, s55, 0
	s_add_u32 s80, s78, 0x10000
	s_addc_u32 s81, s79, 0
	s_waitcnt vmcnt(60)
	global_store_dword v22, v110, s[78:79]
	global_store_dword v22, v111, s[80:81]
	s_lshl_b32 s4, s10, 9
	s_add_u32 s44, s4, 0x3400000
	s_add_u32 s4, s4, 0x3000000
	s_add_u32 s4, s52, s4
	s_addc_u32 s5, s53, 0
	s_add_u32 s44, s52, s44
	s_addc_u32 s45, s53, 0
	s_add_u32 s46, s44, 0x20000
	s_addc_u32 s47, s45, 0
	v_lshlrev_b32_e32 v72, 16, v110
	v_and_b32_e32 v73, 0xffff0000, v110
	v_lshlrev_b32_e32 v74, 16, v111
	v_and_b32_e32 v75, 0xffff0000, v111
	global_store_dwordx2 v23, v[72:73], s[44:45]
	global_store_dwordx2 v23, v[74:75], s[46:47]
	v_lshlrev_b32_e32 v30, 16, v100
	v_and_b32_e32 v31, 0xffff0000, v100
	v_lshlrev_b32_e32 v32, 16, v101
	v_and_b32_e32 v33, 0xffff0000, v101
	v_lshlrev_b32_e32 v34, 16, v102
	v_and_b32_e32 v35, 0xffff0000, v102
	v_lshlrev_b32_e32 v36, 16, v103
	v_and_b32_e32 v37, 0xffff0000, v103
	v_lshlrev_b32_e32 v38, 16, v104
	v_and_b32_e32 v39, 0xffff0000, v104
	v_lshlrev_b32_e32 v40, 16, v105
	v_and_b32_e32 v41, 0xffff0000, v105
	v_lshlrev_b32_e32 v42, 16, v106
	v_and_b32_e32 v43, 0xffff0000, v106
	v_lshlrev_b32_e32 v44, 16, v107
	v_and_b32_e32 v45, 0xffff0000, v107
	v_lshlrev_b32_e32 v46, 16, v108
	v_and_b32_e32 v47, 0xffff0000, v108
	v_lshlrev_b32_e32 v48, 16, v109
	v_and_b32_e32 v49, 0xffff0000, v109
	v_mul_f32_e32 v50, v30, v30
	v_mul_f32_e32 v51, v34, v34
	v_mul_f32_e32 v52, v38, v38
	v_mul_f32_e32 v53, v42, v42
	v_mul_f32_e32 v54, v46, v46
	v_fmac_f32_e32 v50, v31, v31
	v_fmac_f32_e32 v51, v35, v35
	v_fmac_f32_e32 v52, v39, v39
	v_fmac_f32_e32 v53, v43, v43
	v_fmac_f32_e32 v54, v47, v47
	v_fmac_f32_e32 v50, v32, v32
	v_fmac_f32_e32 v51, v36, v36
	v_fmac_f32_e32 v52, v40, v40
	v_fmac_f32_e32 v53, v44, v44
	v_fmac_f32_e32 v54, v48, v48
	v_fmac_f32_e32 v50, v33, v33
	v_fmac_f32_e32 v51, v37, v37
	v_fmac_f32_e32 v52, v41, v41
	v_fmac_f32_e32 v53, v45, v45
	v_fmac_f32_e32 v54, v49, v49
	v_add_f32_dpp v50, v50, v50 quad_perm:[1,0,3,2] row_mask:0xf bank_mask:0xf
	v_add_f32_dpp v51, v51, v51 quad_perm:[1,0,3,2] row_mask:0xf bank_mask:0xf
	v_add_f32_dpp v52, v52, v52 quad_perm:[1,0,3,2] row_mask:0xf bank_mask:0xf
	v_add_f32_dpp v53, v53, v53 quad_perm:[1,0,3,2] row_mask:0xf bank_mask:0xf
	v_add_f32_dpp v54, v54, v54 quad_perm:[1,0,3,2] row_mask:0xf bank_mask:0xf
	v_add_f32_dpp v50, v50, v50 quad_perm:[2,3,0,1] row_mask:0xf bank_mask:0xf
	v_add_f32_dpp v51, v51, v51 quad_perm:[2,3,0,1] row_mask:0xf bank_mask:0xf
	v_add_f32_dpp v52, v52, v52 quad_perm:[2,3,0,1] row_mask:0xf bank_mask:0xf
	v_add_f32_dpp v53, v53, v53 quad_perm:[2,3,0,1] row_mask:0xf bank_mask:0xf
	v_add_f32_dpp v54, v54, v54 quad_perm:[2,3,0,1] row_mask:0xf bank_mask:0xf
	v_add_f32_dpp v50, v50, v50 row_half_mirror row_mask:0xf bank_mask:0xf
	v_add_f32_dpp v51, v51, v51 row_half_mirror row_mask:0xf bank_mask:0xf
	v_add_f32_dpp v52, v52, v52 row_half_mirror row_mask:0xf bank_mask:0xf
	v_add_f32_dpp v53, v53, v53 row_half_mirror row_mask:0xf bank_mask:0xf
	v_add_f32_dpp v54, v54, v54 row_half_mirror row_mask:0xf bank_mask:0xf
	v_add_f32_dpp v50, v50, v50 row_mirror row_mask:0xf bank_mask:0xf
	v_add_f32_dpp v51, v51, v51 row_mirror row_mask:0xf bank_mask:0xf
	v_add_f32_dpp v52, v52, v52 row_mirror row_mask:0xf bank_mask:0xf
	v_add_f32_dpp v53, v53, v53 row_mirror row_mask:0xf bank_mask:0xf
	v_add_f32_dpp v54, v54, v54 row_mirror row_mask:0xf bank_mask:0xf
	v_mov_b32_e32 v55, v50
	v_mov_b32_e32 v56, v51
	v_mov_b32_e32 v57, v52
	v_mov_b32_e32 v58, v53
	v_mov_b32_e32 v59, v54
	s_nop 1
	v_permlane16_swap_b32_e32 v50, v55
	v_permlane16_swap_b32_e32 v51, v56
	v_permlane16_swap_b32_e32 v52, v57
	v_permlane16_swap_b32_e32 v53, v58
	v_permlane16_swap_b32_e32 v54, v59
	v_add_f32_e32 v50, v50, v55
	v_add_f32_e32 v51, v51, v56
	v_add_f32_e32 v52, v52, v57
	v_add_f32_e32 v53, v53, v58
	v_add_f32_e32 v54, v54, v59
	v_fmamk_f32 v50, v50, 0x3c000000, v207
	v_fmamk_f32 v51, v51, 0x3c000000, v207
	v_fmamk_f32 v52, v52, 0x3c000000, v207
	v_fmamk_f32 v53, v53, 0x3c000000, v207
	v_fmamk_f32 v54, v54, 0x3c000000, v207
	v_rsq_f32_e32 v55, v50
	v_rsq_f32_e32 v56, v51
	v_rsq_f32_e32 v57, v52
	v_rsq_f32_e32 v58, v53
	v_rsq_f32_e32 v59, v54
	v_mul_f32_e32 v50, v50, v55
	v_mul_f32_e32 v51, v51, v56
	v_mul_f32_e32 v52, v52, v57
	v_mul_f32_e32 v53, v53, v58
	v_mul_f32_e32 v54, v54, v59
	v_fma_f32 v50, -v50, v55, 1.0
	v_fma_f32 v51, -v51, v56, 1.0
	v_fma_f32 v52, -v52, v57, 1.0
	v_fma_f32 v53, -v53, v58, 1.0
	v_fma_f32 v54, -v54, v59, 1.0
	v_mul_f32_e32 v50, 0.5, v50
	v_mul_f32_e32 v51, 0.5, v51
	v_mul_f32_e32 v52, 0.5, v52
	v_mul_f32_e32 v53, 0.5, v53
	v_mul_f32_e32 v54, 0.5, v54
	v_fmac_f32_e32 v55, v55, v50
	v_fmac_f32_e32 v56, v56, v51
	v_fmac_f32_e32 v57, v57, v52
	v_fmac_f32_e32 v58, v58, v53
	v_fmac_f32_e32 v59, v59, v54
	v_mul_f32_e32 v30, v30, v55
	v_mul_f32_e32 v31, v31, v55
	v_mul_f32_e32 v32, v32, v55
	v_mul_f32_e32 v33, v33, v55
	v_mul_f32_e32 v30, v30, v4
	v_mul_f32_e32 v31, v31, v5
	v_mul_f32_e32 v32, v32, v6
	v_mul_f32_e32 v33, v33, v7
	v_cvt_pk_bf16_f32 v68, v30, v31
	v_cvt_pk_bf16_f32 v69, v32, v33
	global_store_dword v18, v68, s[74:75] offset:0
	global_store_dword v18, v69, s[74:75] offset:64
	v_mul_f32_e32 v34, v34, v56
	v_mul_f32_e32 v35, v35, v56
	v_mul_f32_e32 v36, v36, v56
	v_mul_f32_e32 v37, v37, v56
	v_mul_f32_e32 v34, v34, v4
	v_mul_f32_e32 v35, v35, v5
	v_mul_f32_e32 v36, v36, v6
	v_mul_f32_e32 v37, v37, v7
	v_cvt_pk_bf16_f32 v68, v34, v35
	v_cvt_pk_bf16_f32 v69, v36, v37
	global_store_dword v18, v68, s[74:75] offset:512
	global_store_dword v18, v69, s[74:75] offset:576
	v_mul_f32_e32 v38, v38, v57
	v_mul_f32_e32 v39, v39, v57
	v_mul_f32_e32 v40, v40, v57
	v_mul_f32_e32 v41, v41, v57
	v_mul_f32_e32 v38, v38, v4
	v_mul_f32_e32 v39, v39, v5
	v_mul_f32_e32 v40, v40, v6
	v_mul_f32_e32 v41, v41, v7
	v_cvt_pk_bf16_f32 v68, v38, v39
	v_cvt_pk_bf16_f32 v69, v40, v41
	global_store_dword v18, v68, s[74:75] offset:1024
	global_store_dword v18, v69, s[74:75] offset:1088
	v_mul_f32_e32 v42, v42, v58
	v_mul_f32_e32 v43, v43, v58
	v_mul_f32_e32 v44, v44, v58
	v_mul_f32_e32 v45, v45, v58
	v_mul_f32_e32 v42, v42, v4
	v_mul_f32_e32 v43, v43, v5
	v_mul_f32_e32 v44, v44, v6
	v_mul_f32_e32 v45, v45, v7
	v_cvt_pk_bf16_f32 v68, v42, v43
	v_cvt_pk_bf16_f32 v69, v44, v45
	global_store_dword v18, v68, s[74:75] offset:1536
	global_store_dword v18, v69, s[74:75] offset:1600
	v_mul_f32_e32 v46, v46, v59
	v_mul_f32_e32 v47, v47, v59
	v_mul_f32_e32 v48, v48, v59
	v_mul_f32_e32 v49, v49, v59
	v_mul_f32_e32 v46, v46, v8
	v_mul_f32_e32 v47, v47, v9
	v_mul_f32_e32 v48, v48, v10
	v_mul_f32_e32 v49, v49, v11
	global_store_dwordx2 v21, v[46:47], s[4:5]
	global_store_dwordx2 v21, v[48:49], s[4:5] offset:128
	v_cvt_pk_bf16_f32 v68, v46, v47
	v_cvt_pk_bf16_f32 v69, v48, v49
	global_store_dword v20, v68, s[76:77]
	global_store_dword v20, v69, s[76:77] offset:64
	s_add_i32 s71, s70, 0x800
	s_lshr_b32 s11, s71, 8
	s_and_b32 s10, s71, 0xff
	s_lshl_b32 s11, s11, 9
	s_add_i32 s10, s10, s11
	s_lshl_b32 s74, s71, 11
	s_add_u32 s74, s74, 0x87c8000
	s_add_u32 s74, s54, s74
	s_addc_u32 s75, s55, 0
	s_lshl_b32 s76, s10, 8
	s_add_u32 s78, s76, 0x12bc8000
	s_add_u32 s76, s76, 0x129c8000
	s_add_u32 s76, s54, s76
	s_addc_u32 s77, s55, 0
	s_add_u32 s78, s54, s78
	s_addc_u32 s79, s55, 0
	s_add_u32 s80, s78, 0x10000
	s_addc_u32 s81, s79, 0
	s_waitcnt vmcnt(63)
	global_store_dword v22, v122, s[78:79]
	global_store_dword v22, v123, s[80:81]
	s_lshl_b32 s4, s10, 9
	s_add_u32 s44, s4, 0x3400000
	s_add_u32 s4, s4, 0x3000000
	s_add_u32 s4, s52, s4
	s_addc_u32 s5, s53, 0
	s_add_u32 s44, s52, s44
	s_addc_u32 s45, s53, 0
	s_add_u32 s46, s44, 0x20000
	s_addc_u32 s47, s45, 0
	v_lshlrev_b32_e32 v72, 16, v122
	v_and_b32_e32 v73, 0xffff0000, v122
	v_lshlrev_b32_e32 v74, 16, v123
	v_and_b32_e32 v75, 0xffff0000, v123
	global_store_dwordx2 v23, v[72:73], s[44:45]
	global_store_dwordx2 v23, v[74:75], s[46:47]
	v_lshlrev_b32_e32 v30, 16, v112
	v_and_b32_e32 v31, 0xffff0000, v112
	v_lshlrev_b32_e32 v32, 16, v113
	v_and_b32_e32 v33, 0xffff0000, v113
	v_lshlrev_b32_e32 v34, 16, v114
	v_and_b32_e32 v35, 0xffff0000, v114
	v_lshlrev_b32_e32 v36, 16, v115
	v_and_b32_e32 v37, 0xffff0000, v115
	v_lshlrev_b32_e32 v38, 16, v116
	v_and_b32_e32 v39, 0xffff0000, v116
	v_lshlrev_b32_e32 v40, 16, v117
	v_and_b32_e32 v41, 0xffff0000, v117
	v_lshlrev_b32_e32 v42, 16, v118
	v_and_b32_e32 v43, 0xffff0000, v118
	v_lshlrev_b32_e32 v44, 16, v119
	v_and_b32_e32 v45, 0xffff0000, v119
	v_lshlrev_b32_e32 v46, 16, v120
	v_and_b32_e32 v47, 0xffff0000, v120
	v_lshlrev_b32_e32 v48, 16, v121
	v_and_b32_e32 v49, 0xffff0000, v121
	v_mul_f32_e32 v50, v30, v30
	v_mul_f32_e32 v51, v34, v34
	v_mul_f32_e32 v52, v38, v38
	v_mul_f32_e32 v53, v42, v42
	v_mul_f32_e32 v54, v46, v46
	v_fmac_f32_e32 v50, v31, v31
	v_fmac_f32_e32 v51, v35, v35
	v_fmac_f32_e32 v52, v39, v39
	v_fmac_f32_e32 v53, v43, v43
	v_fmac_f32_e32 v54, v47, v47
	v_fmac_f32_e32 v50, v32, v32
	v_fmac_f32_e32 v51, v36, v36
	v_fmac_f32_e32 v52, v40, v40
	v_fmac_f32_e32 v53, v44, v44
	v_fmac_f32_e32 v54, v48, v48
	v_fmac_f32_e32 v50, v33, v33
	v_fmac_f32_e32 v51, v37, v37
	v_fmac_f32_e32 v52, v41, v41
	v_fmac_f32_e32 v53, v45, v45
	v_fmac_f32_e32 v54, v49, v49
	v_add_f32_dpp v50, v50, v50 quad_perm:[1,0,3,2] row_mask:0xf bank_mask:0xf
	v_add_f32_dpp v51, v51, v51 quad_perm:[1,0,3,2] row_mask:0xf bank_mask:0xf
	v_add_f32_dpp v52, v52, v52 quad_perm:[1,0,3,2] row_mask:0xf bank_mask:0xf
	v_add_f32_dpp v53, v53, v53 quad_perm:[1,0,3,2] row_mask:0xf bank_mask:0xf
	v_add_f32_dpp v54, v54, v54 quad_perm:[1,0,3,2] row_mask:0xf bank_mask:0xf
	v_add_f32_dpp v50, v50, v50 quad_perm:[2,3,0,1] row_mask:0xf bank_mask:0xf
	v_add_f32_dpp v51, v51, v51 quad_perm:[2,3,0,1] row_mask:0xf bank_mask:0xf
	v_add_f32_dpp v52, v52, v52 quad_perm:[2,3,0,1] row_mask:0xf bank_mask:0xf
	v_add_f32_dpp v53, v53, v53 quad_perm:[2,3,0,1] row_mask:0xf bank_mask:0xf
	v_add_f32_dpp v54, v54, v54 quad_perm:[2,3,0,1] row_mask:0xf bank_mask:0xf
	v_add_f32_dpp v50, v50, v50 row_half_mirror row_mask:0xf bank_mask:0xf
	v_add_f32_dpp v51, v51, v51 row_half_mirror row_mask:0xf bank_mask:0xf
	v_add_f32_dpp v52, v52, v52 row_half_mirror row_mask:0xf bank_mask:0xf
	v_add_f32_dpp v53, v53, v53 row_half_mirror row_mask:0xf bank_mask:0xf
	v_add_f32_dpp v54, v54, v54 row_half_mirror row_mask:0xf bank_mask:0xf
	v_add_f32_dpp v50, v50, v50 row_mirror row_mask:0xf bank_mask:0xf
	v_add_f32_dpp v51, v51, v51 row_mirror row_mask:0xf bank_mask:0xf
	v_add_f32_dpp v52, v52, v52 row_mirror row_mask:0xf bank_mask:0xf
	v_add_f32_dpp v53, v53, v53 row_mirror row_mask:0xf bank_mask:0xf
	v_add_f32_dpp v54, v54, v54 row_mirror row_mask:0xf bank_mask:0xf
	v_mov_b32_e32 v55, v50
	v_mov_b32_e32 v56, v51
	v_mov_b32_e32 v57, v52
	v_mov_b32_e32 v58, v53
	v_mov_b32_e32 v59, v54
	s_nop 1
	v_permlane16_swap_b32_e32 v50, v55
	v_permlane16_swap_b32_e32 v51, v56
	v_permlane16_swap_b32_e32 v52, v57
	v_permlane16_swap_b32_e32 v53, v58
	v_permlane16_swap_b32_e32 v54, v59
	v_add_f32_e32 v50, v50, v55
	v_add_f32_e32 v51, v51, v56
	v_add_f32_e32 v52, v52, v57
	v_add_f32_e32 v53, v53, v58
	v_add_f32_e32 v54, v54, v59
	v_fmamk_f32 v50, v50, 0x3c000000, v207
	v_fmamk_f32 v51, v51, 0x3c000000, v207
	v_fmamk_f32 v52, v52, 0x3c000000, v207
	v_fmamk_f32 v53, v53, 0x3c000000, v207
	v_fmamk_f32 v54, v54, 0x3c000000, v207
	v_rsq_f32_e32 v55, v50
	v_rsq_f32_e32 v56, v51
	v_rsq_f32_e32 v57, v52
	v_rsq_f32_e32 v58, v53
	v_rsq_f32_e32 v59, v54
	v_mul_f32_e32 v50, v50, v55
	v_mul_f32_e32 v51, v51, v56
	v_mul_f32_e32 v52, v52, v57
	v_mul_f32_e32 v53, v53, v58
	v_mul_f32_e32 v54, v54, v59
	v_fma_f32 v50, -v50, v55, 1.0
	v_fma_f32 v51, -v51, v56, 1.0
	v_fma_f32 v52, -v52, v57, 1.0
	v_fma_f32 v53, -v53, v58, 1.0
	v_fma_f32 v54, -v54, v59, 1.0
	v_mul_f32_e32 v50, 0.5, v50
	v_mul_f32_e32 v51, 0.5, v51
	v_mul_f32_e32 v52, 0.5, v52
	v_mul_f32_e32 v53, 0.5, v53
	v_mul_f32_e32 v54, 0.5, v54
	v_fmac_f32_e32 v55, v55, v50
	v_fmac_f32_e32 v56, v56, v51
	v_fmac_f32_e32 v57, v57, v52
	v_fmac_f32_e32 v58, v58, v53
	v_fmac_f32_e32 v59, v59, v54
	v_mul_f32_e32 v30, v30, v55
	v_mul_f32_e32 v31, v31, v55
	v_mul_f32_e32 v32, v32, v55
	v_mul_f32_e32 v33, v33, v55
	v_mul_f32_e32 v30, v30, v4
	v_mul_f32_e32 v31, v31, v5
	v_mul_f32_e32 v32, v32, v6
	v_mul_f32_e32 v33, v33, v7
	v_cvt_pk_bf16_f32 v68, v30, v31
	v_cvt_pk_bf16_f32 v69, v32, v33
	global_store_dword v18, v68, s[74:75] offset:0
	global_store_dword v18, v69, s[74:75] offset:64
	v_mul_f32_e32 v34, v34, v56
	v_mul_f32_e32 v35, v35, v56
	v_mul_f32_e32 v36, v36, v56
	v_mul_f32_e32 v37, v37, v56
	v_mul_f32_e32 v34, v34, v4
	v_mul_f32_e32 v35, v35, v5
	v_mul_f32_e32 v36, v36, v6
	v_mul_f32_e32 v37, v37, v7
	v_cvt_pk_bf16_f32 v68, v34, v35
	v_cvt_pk_bf16_f32 v69, v36, v37
	global_store_dword v18, v68, s[74:75] offset:512
	global_store_dword v18, v69, s[74:75] offset:576
	v_mul_f32_e32 v38, v38, v57
	v_mul_f32_e32 v39, v39, v57
	v_mul_f32_e32 v40, v40, v57
	v_mul_f32_e32 v41, v41, v57
	v_mul_f32_e32 v38, v38, v4
	v_mul_f32_e32 v39, v39, v5
	v_mul_f32_e32 v40, v40, v6
	v_mul_f32_e32 v41, v41, v7
	v_cvt_pk_bf16_f32 v68, v38, v39
	v_cvt_pk_bf16_f32 v69, v40, v41
	global_store_dword v18, v68, s[74:75] offset:1024
	global_store_dword v18, v69, s[74:75] offset:1088
	v_mul_f32_e32 v42, v42, v58
	v_mul_f32_e32 v43, v43, v58
	v_mul_f32_e32 v44, v44, v58
	v_mul_f32_e32 v45, v45, v58
	v_mul_f32_e32 v42, v42, v4
	v_mul_f32_e32 v43, v43, v5
	v_mul_f32_e32 v44, v44, v6
	v_mul_f32_e32 v45, v45, v7
	v_cvt_pk_bf16_f32 v68, v42, v43
	v_cvt_pk_bf16_f32 v69, v44, v45
	global_store_dword v18, v68, s[74:75] offset:1536
	global_store_dword v18, v69, s[74:75] offset:1600
	v_mul_f32_e32 v46, v46, v59
	v_mul_f32_e32 v47, v47, v59
	v_mul_f32_e32 v48, v48, v59
	v_mul_f32_e32 v49, v49, v59
	v_mul_f32_e32 v46, v46, v8
	v_mul_f32_e32 v47, v47, v9
	v_mul_f32_e32 v48, v48, v10
	v_mul_f32_e32 v49, v49, v11
	global_store_dwordx2 v21, v[46:47], s[4:5]
	global_store_dwordx2 v21, v[48:49], s[4:5] offset:128
	v_cvt_pk_bf16_f32 v68, v46, v47
	v_cvt_pk_bf16_f32 v69, v48, v49
	global_store_dword v20, v68, s[76:77]
	global_store_dword v20, v69, s[76:77] offset:64
	s_add_i32 s71, s70, 0x1000
	s_bfe_u32 s40, s71, 0x60006
	s_and_b32 s41, s71, 63
	s_sub_i32 s10, s71, 0x1000
	s_lshr_b32 s11, s10, 12
	s_and_b32 s10, s10, 0xfff
	s_mulk_i32 s11, 0x2200
	s_add_i32 s10, s10, s11
	s_addk_i32 s10, 0x100
	s_lshl_b32 s74, s71, 11
	s_add_u32 s74, s74, 0x87c8000
	s_add_u32 s74, s54, s74
	s_addc_u32 s75, s55, 0
	s_lshl_b32 s76, s10, 8
	s_add_u32 s78, s76, 0x13208000
	s_add_u32 s76, s76, 0x12dc8000
	s_add_u32 s76, s54, s76
	s_addc_u32 s77, s55, 0
	s_add_u32 s78, s54, s78
	s_addc_u32 s79, s55, 0
	s_add_u32 s80, s78, 0x110000
	s_addc_u32 s81, s79, 0
	s_waitcnt vmcnt(63)
	global_store_dword v22, v134, s[78:79]
	global_store_dword v22, v135, s[80:81]
	v_lshlrev_b32_e32 v30, 16, v124
	v_and_b32_e32 v31, 0xffff0000, v124
	v_lshlrev_b32_e32 v32, 16, v125
	v_and_b32_e32 v33, 0xffff0000, v125
	v_lshlrev_b32_e32 v34, 16, v126
	v_and_b32_e32 v35, 0xffff0000, v126
	v_lshlrev_b32_e32 v36, 16, v127
	v_and_b32_e32 v37, 0xffff0000, v127
	v_lshlrev_b32_e32 v38, 16, v128
	v_and_b32_e32 v39, 0xffff0000, v128
	v_lshlrev_b32_e32 v40, 16, v129
	v_and_b32_e32 v41, 0xffff0000, v129
	v_lshlrev_b32_e32 v42, 16, v130
	v_and_b32_e32 v43, 0xffff0000, v130
	v_lshlrev_b32_e32 v44, 16, v131
	v_and_b32_e32 v45, 0xffff0000, v131
	v_lshlrev_b32_e32 v46, 16, v132
	v_and_b32_e32 v47, 0xffff0000, v132
	v_lshlrev_b32_e32 v48, 16, v133
	v_and_b32_e32 v49, 0xffff0000, v133
	v_mul_f32_e32 v50, v30, v30
	v_mul_f32_e32 v51, v34, v34
	v_mul_f32_e32 v52, v38, v38
	v_mul_f32_e32 v53, v42, v42
	v_mul_f32_e32 v54, v46, v46
	v_fmac_f32_e32 v50, v31, v31
	v_fmac_f32_e32 v51, v35, v35
	v_fmac_f32_e32 v52, v39, v39
	v_fmac_f32_e32 v53, v43, v43
	v_fmac_f32_e32 v54, v47, v47
	v_fmac_f32_e32 v50, v32, v32
	v_fmac_f32_e32 v51, v36, v36
	v_fmac_f32_e32 v52, v40, v40
	v_fmac_f32_e32 v53, v44, v44
	v_fmac_f32_e32 v54, v48, v48
	v_fmac_f32_e32 v50, v33, v33
	v_fmac_f32_e32 v51, v37, v37
	v_fmac_f32_e32 v52, v41, v41
	v_fmac_f32_e32 v53, v45, v45
	v_fmac_f32_e32 v54, v49, v49
	v_add_f32_dpp v50, v50, v50 quad_perm:[1,0,3,2] row_mask:0xf bank_mask:0xf
	v_add_f32_dpp v51, v51, v51 quad_perm:[1,0,3,2] row_mask:0xf bank_mask:0xf
	v_add_f32_dpp v52, v52, v52 quad_perm:[1,0,3,2] row_mask:0xf bank_mask:0xf
	v_add_f32_dpp v53, v53, v53 quad_perm:[1,0,3,2] row_mask:0xf bank_mask:0xf
	v_add_f32_dpp v54, v54, v54 quad_perm:[1,0,3,2] row_mask:0xf bank_mask:0xf
	v_add_f32_dpp v50, v50, v50 quad_perm:[2,3,0,1] row_mask:0xf bank_mask:0xf
	v_add_f32_dpp v51, v51, v51 quad_perm:[2,3,0,1] row_mask:0xf bank_mask:0xf
	v_add_f32_dpp v52, v52, v52 quad_perm:[2,3,0,1] row_mask:0xf bank_mask:0xf
	v_add_f32_dpp v53, v53, v53 quad_perm:[2,3,0,1] row_mask:0xf bank_mask:0xf
	v_add_f32_dpp v54, v54, v54 quad_perm:[2,3,0,1] row_mask:0xf bank_mask:0xf
	v_add_f32_dpp v50, v50, v50 row_half_mirror row_mask:0xf bank_mask:0xf
	v_add_f32_dpp v51, v51, v51 row_half_mirror row_mask:0xf bank_mask:0xf
	v_add_f32_dpp v52, v52, v52 row_half_mirror row_mask:0xf bank_mask:0xf
	v_add_f32_dpp v53, v53, v53 row_half_mirror row_mask:0xf bank_mask:0xf
	v_add_f32_dpp v54, v54, v54 row_half_mirror row_mask:0xf bank_mask:0xf
	v_add_f32_dpp v50, v50, v50 row_mirror row_mask:0xf bank_mask:0xf
	v_add_f32_dpp v51, v51, v51 row_mirror row_mask:0xf bank_mask:0xf
	v_add_f32_dpp v52, v52, v52 row_mirror row_mask:0xf bank_mask:0xf
	v_add_f32_dpp v53, v53, v53 row_mirror row_mask:0xf bank_mask:0xf
	v_add_f32_dpp v54, v54, v54 row_mirror row_mask:0xf bank_mask:0xf
	v_mov_b32_e32 v55, v50
	v_mov_b32_e32 v56, v51
	v_mov_b32_e32 v57, v52
	v_mov_b32_e32 v58, v53
	v_mov_b32_e32 v59, v54
	s_nop 1
	v_permlane16_swap_b32_e32 v50, v55
	v_permlane16_swap_b32_e32 v51, v56
	v_permlane16_swap_b32_e32 v52, v57
	v_permlane16_swap_b32_e32 v53, v58
	v_permlane16_swap_b32_e32 v54, v59
	v_add_f32_e32 v50, v50, v55
	v_add_f32_e32 v51, v51, v56
	v_add_f32_e32 v52, v52, v57
	v_add_f32_e32 v53, v53, v58
	v_add_f32_e32 v54, v54, v59
	v_fmamk_f32 v50, v50, 0x3c000000, v207
	v_fmamk_f32 v51, v51, 0x3c000000, v207
	v_fmamk_f32 v52, v52, 0x3c000000, v207
	v_fmamk_f32 v53, v53, 0x3c000000, v207
	v_fmamk_f32 v54, v54, 0x3c000000, v207
	v_rsq_f32_e32 v55, v50
	v_rsq_f32_e32 v56, v51
	v_rsq_f32_e32 v57, v52
	v_rsq_f32_e32 v58, v53
	v_rsq_f32_e32 v59, v54
	v_mul_f32_e32 v50, v50, v55
	v_mul_f32_e32 v51, v51, v56
	v_mul_f32_e32 v52, v52, v57
	v_mul_f32_e32 v53, v53, v58
	v_mul_f32_e32 v54, v54, v59
	v_fma_f32 v50, -v50, v55, 1.0
	v_fma_f32 v51, -v51, v56, 1.0
	v_fma_f32 v52, -v52, v57, 1.0
	v_fma_f32 v53, -v53, v58, 1.0
	v_fma_f32 v54, -v54, v59, 1.0
	v_mul_f32_e32 v50, 0.5, v50
	v_mul_f32_e32 v51, 0.5, v51
	v_mul_f32_e32 v52, 0.5, v52
	v_mul_f32_e32 v53, 0.5, v53
	v_mul_f32_e32 v54, 0.5, v54
	v_fmac_f32_e32 v55, v55, v50
	v_fmac_f32_e32 v56, v56, v51
	v_fmac_f32_e32 v57, v57, v52
	v_fmac_f32_e32 v58, v58, v53
	v_fmac_f32_e32 v59, v59, v54
	v_mov_b32_e32 v70, s40
	v_mov_b32_e32 v71, s41
	v_cndmask_b32_e64 v70, v71, v70, s[42:43]
	v_cvt_f32_ubyte0_e32 v70, v70
	v_mul_f32_e32 v60, v26, v70
	v_mul_f32_e32 v62, v27, v70
	v_mul_f32_e32 v61, 0.15915494, v60
	v_mul_f32_e32 v63, 0.15915494, v62
	v_rndne_f32_e32 v61, v61
	v_rndne_f32_e32 v63, v63
	v_fmac_f32_e32 v60, 0xc0c90fdb, v61
	v_fmac_f32_e32 v62, 0xc0c90fdb, v63
	v_fmac_f32_e32 v60, 0x343bbd2e, v61
	v_fmac_f32_e32 v62, 0x343bbd2e, v63
	v_mul_f32_e32 v60, 0.15915494, v60
	v_mul_f32_e32 v62, 0.15915494, v62
	v_sin_f32_e32 v61, v60
	v_sin_f32_e32 v63, v62
	v_cos_f32_e32 v60, v60
	v_cos_f32_e32 v62, v62
	v_mul_f32_e32 v30, v30, v55
	v_mul_f32_e32 v31, v31, v55
	v_mul_f32_e32 v32, v32, v55
	v_mul_f32_e32 v33, v33, v55
	v_mul_f32_e32 v30, v30, v4
	v_mul_f32_e32 v31, v31, v5
	v_mul_f32_e32 v32, v32, v6
	v_mul_f32_e32 v33, v33, v7
	v_mul_f32_e32 v64, v61, v32
	v_mul_f32_e32 v65, v63, v33
	v_mul_f32_e32 v66, v60, v32
	v_mul_f32_e32 v67, v62, v33
	v_fma_f32 v64, v60, v30, -v64
	v_fma_f32 v65, v62, v31, -v65
	v_fmac_f32_e32 v66, v61, v30
	v_fmac_f32_e32 v67, v63, v31
	v_cvt_pk_bf16_f32 v68, v64, v65
	v_cvt_pk_bf16_f32 v69, v66, v67
	global_store_dword v18, v68, s[74:75] offset:0
	global_store_dword v18, v69, s[74:75] offset:64
	v_mul_f32_e32 v34, v34, v56
	v_mul_f32_e32 v35, v35, v56
	v_mul_f32_e32 v36, v36, v56
	v_mul_f32_e32 v37, v37, v56
	v_mul_f32_e32 v34, v34, v4
	v_mul_f32_e32 v35, v35, v5
	v_mul_f32_e32 v36, v36, v6
	v_mul_f32_e32 v37, v37, v7
	v_mul_f32_e32 v64, v61, v36
	v_mul_f32_e32 v65, v63, v37
	v_mul_f32_e32 v66, v60, v36
	v_mul_f32_e32 v67, v62, v37
	v_fma_f32 v64, v60, v34, -v64
	v_fma_f32 v65, v62, v35, -v65
	v_fmac_f32_e32 v66, v61, v34
	v_fmac_f32_e32 v67, v63, v35
	v_cvt_pk_bf16_f32 v68, v64, v65
	v_cvt_pk_bf16_f32 v69, v66, v67
	global_store_dword v18, v68, s[74:75] offset:512
	global_store_dword v18, v69, s[74:75] offset:576
	v_mul_f32_e32 v38, v38, v57
	v_mul_f32_e32 v39, v39, v57
	v_mul_f32_e32 v40, v40, v57
	v_mul_f32_e32 v41, v41, v57
	v_mul_f32_e32 v38, v38, v4
	v_mul_f32_e32 v39, v39, v5
	v_mul_f32_e32 v40, v40, v6
	v_mul_f32_e32 v41, v41, v7
	v_mul_f32_e32 v64, v61, v40
	v_mul_f32_e32 v65, v63, v41
	v_mul_f32_e32 v66, v60, v40
	v_mul_f32_e32 v67, v62, v41
	v_fma_f32 v64, v60, v38, -v64
	v_fma_f32 v65, v62, v39, -v65
	v_fmac_f32_e32 v66, v61, v38
	v_fmac_f32_e32 v67, v63, v39
	v_cvt_pk_bf16_f32 v68, v64, v65
	v_cvt_pk_bf16_f32 v69, v66, v67
	global_store_dword v18, v68, s[74:75] offset:1024
	global_store_dword v18, v69, s[74:75] offset:1088
	v_mul_f32_e32 v42, v42, v58
	v_mul_f32_e32 v43, v43, v58
	v_mul_f32_e32 v44, v44, v58
	v_mul_f32_e32 v45, v45, v58
	v_mul_f32_e32 v42, v42, v4
	v_mul_f32_e32 v43, v43, v5
	v_mul_f32_e32 v44, v44, v6
	v_mul_f32_e32 v45, v45, v7
	v_mul_f32_e32 v64, v61, v44
	v_mul_f32_e32 v65, v63, v45
	v_mul_f32_e32 v66, v60, v44
	v_mul_f32_e32 v67, v62, v45
	v_fma_f32 v64, v60, v42, -v64
	v_fma_f32 v65, v62, v43, -v65
	v_fmac_f32_e32 v66, v61, v42
	v_fmac_f32_e32 v67, v63, v43
	v_cvt_pk_bf16_f32 v68, v64, v65
	v_cvt_pk_bf16_f32 v69, v66, v67
	global_store_dword v18, v68, s[74:75] offset:1536
	global_store_dword v18, v69, s[74:75] offset:1600
	v_mul_f32_e32 v46, v46, v59
	v_mul_f32_e32 v47, v47, v59
	v_mul_f32_e32 v48, v48, v59
	v_mul_f32_e32 v49, v49, v59
	v_mul_f32_e32 v46, v46, v8
	v_mul_f32_e32 v47, v47, v9
	v_mul_f32_e32 v48, v48, v10
	v_mul_f32_e32 v49, v49, v11
	v_mul_f32_e32 v64, v61, v48
	v_mul_f32_e32 v65, v63, v49
	v_mul_f32_e32 v66, v60, v48
	v_mul_f32_e32 v67, v62, v49
	v_fma_f32 v64, v60, v46, -v64
	v_fma_f32 v65, v62, v47, -v65
	v_fmac_f32_e32 v66, v61, v46
	v_fmac_f32_e32 v67, v63, v47
	v_cvt_pk_bf16_f32 v68, v64, v65
	v_cvt_pk_bf16_f32 v69, v66, v67
	global_store_dword v19, v68, s[76:77]
	global_store_dword v19, v69, s[76:77] offset:64
	s_add_i32 s71, s70, 0x1800
	s_bfe_u32 s40, s71, 0x60006
	s_and_b32 s41, s71, 63
	s_sub_i32 s10, s71, 0x1000
	s_lshr_b32 s11, s10, 12
	s_and_b32 s10, s10, 0xfff
	s_mulk_i32 s11, 0x2200
	s_add_i32 s10, s10, s11
	s_addk_i32 s10, 0x100
	s_lshl_b32 s74, s71, 11
	s_add_u32 s74, s74, 0x87c8000
	s_add_u32 s74, s54, s74
	s_addc_u32 s75, s55, 0
	s_lshl_b32 s76, s10, 8
	s_add_u32 s78, s76, 0x13208000
	s_add_u32 s76, s76, 0x12dc8000
	s_add_u32 s76, s54, s76
	s_addc_u32 s77, s55, 0
	s_add_u32 s78, s54, s78
	s_addc_u32 s79, s55, 0
	s_add_u32 s80, s78, 0x110000
	s_addc_u32 s81, s79, 0
	s_waitcnt vmcnt(63)
	global_store_dword v22, v146, s[78:79]
	global_store_dword v22, v147, s[80:81]
	v_lshlrev_b32_e32 v30, 16, v136
	v_and_b32_e32 v31, 0xffff0000, v136
	v_lshlrev_b32_e32 v32, 16, v137
	v_and_b32_e32 v33, 0xffff0000, v137
	v_lshlrev_b32_e32 v34, 16, v138
	v_and_b32_e32 v35, 0xffff0000, v138
	v_lshlrev_b32_e32 v36, 16, v139
	v_and_b32_e32 v37, 0xffff0000, v139
	v_lshlrev_b32_e32 v38, 16, v140
	v_and_b32_e32 v39, 0xffff0000, v140
	v_lshlrev_b32_e32 v40, 16, v141
	v_and_b32_e32 v41, 0xffff0000, v141
	v_lshlrev_b32_e32 v42, 16, v142
	v_and_b32_e32 v43, 0xffff0000, v142
	v_lshlrev_b32_e32 v44, 16, v143
	v_and_b32_e32 v45, 0xffff0000, v143
	v_lshlrev_b32_e32 v46, 16, v144
	v_and_b32_e32 v47, 0xffff0000, v144
	v_lshlrev_b32_e32 v48, 16, v145
	v_and_b32_e32 v49, 0xffff0000, v145
	v_mul_f32_e32 v50, v30, v30
	v_mul_f32_e32 v51, v34, v34
	v_mul_f32_e32 v52, v38, v38
	v_mul_f32_e32 v53, v42, v42
	v_mul_f32_e32 v54, v46, v46
	v_fmac_f32_e32 v50, v31, v31
	v_fmac_f32_e32 v51, v35, v35
	v_fmac_f32_e32 v52, v39, v39
	v_fmac_f32_e32 v53, v43, v43
	v_fmac_f32_e32 v54, v47, v47
	v_fmac_f32_e32 v50, v32, v32
	v_fmac_f32_e32 v51, v36, v36
	v_fmac_f32_e32 v52, v40, v40
	v_fmac_f32_e32 v53, v44, v44
	v_fmac_f32_e32 v54, v48, v48
	v_fmac_f32_e32 v50, v33, v33
	v_fmac_f32_e32 v51, v37, v37
	v_fmac_f32_e32 v52, v41, v41
	v_fmac_f32_e32 v53, v45, v45
	v_fmac_f32_e32 v54, v49, v49
	v_add_f32_dpp v50, v50, v50 quad_perm:[1,0,3,2] row_mask:0xf bank_mask:0xf
	v_add_f32_dpp v51, v51, v51 quad_perm:[1,0,3,2] row_mask:0xf bank_mask:0xf
	v_add_f32_dpp v52, v52, v52 quad_perm:[1,0,3,2] row_mask:0xf bank_mask:0xf
	v_add_f32_dpp v53, v53, v53 quad_perm:[1,0,3,2] row_mask:0xf bank_mask:0xf
	v_add_f32_dpp v54, v54, v54 quad_perm:[1,0,3,2] row_mask:0xf bank_mask:0xf
	v_add_f32_dpp v50, v50, v50 quad_perm:[2,3,0,1] row_mask:0xf bank_mask:0xf
	v_add_f32_dpp v51, v51, v51 quad_perm:[2,3,0,1] row_mask:0xf bank_mask:0xf
	v_add_f32_dpp v52, v52, v52 quad_perm:[2,3,0,1] row_mask:0xf bank_mask:0xf
	v_add_f32_dpp v53, v53, v53 quad_perm:[2,3,0,1] row_mask:0xf bank_mask:0xf
	v_add_f32_dpp v54, v54, v54 quad_perm:[2,3,0,1] row_mask:0xf bank_mask:0xf
	v_add_f32_dpp v50, v50, v50 row_half_mirror row_mask:0xf bank_mask:0xf
	v_add_f32_dpp v51, v51, v51 row_half_mirror row_mask:0xf bank_mask:0xf
	v_add_f32_dpp v52, v52, v52 row_half_mirror row_mask:0xf bank_mask:0xf
	v_add_f32_dpp v53, v53, v53 row_half_mirror row_mask:0xf bank_mask:0xf
	v_add_f32_dpp v54, v54, v54 row_half_mirror row_mask:0xf bank_mask:0xf
	v_add_f32_dpp v50, v50, v50 row_mirror row_mask:0xf bank_mask:0xf
	v_add_f32_dpp v51, v51, v51 row_mirror row_mask:0xf bank_mask:0xf
	v_add_f32_dpp v52, v52, v52 row_mirror row_mask:0xf bank_mask:0xf
	v_add_f32_dpp v53, v53, v53 row_mirror row_mask:0xf bank_mask:0xf
	v_add_f32_dpp v54, v54, v54 row_mirror row_mask:0xf bank_mask:0xf
	v_mov_b32_e32 v55, v50
	v_mov_b32_e32 v56, v51
	v_mov_b32_e32 v57, v52
	v_mov_b32_e32 v58, v53
	v_mov_b32_e32 v59, v54
	s_nop 1
	v_permlane16_swap_b32_e32 v50, v55
	v_permlane16_swap_b32_e32 v51, v56
	v_permlane16_swap_b32_e32 v52, v57
	v_permlane16_swap_b32_e32 v53, v58
	v_permlane16_swap_b32_e32 v54, v59
	v_add_f32_e32 v50, v50, v55
	v_add_f32_e32 v51, v51, v56
	v_add_f32_e32 v52, v52, v57
	v_add_f32_e32 v53, v53, v58
	v_add_f32_e32 v54, v54, v59
	v_fmamk_f32 v50, v50, 0x3c000000, v207
	v_fmamk_f32 v51, v51, 0x3c000000, v207
	v_fmamk_f32 v52, v52, 0x3c000000, v207
	v_fmamk_f32 v53, v53, 0x3c000000, v207
	v_fmamk_f32 v54, v54, 0x3c000000, v207
	v_rsq_f32_e32 v55, v50
	v_rsq_f32_e32 v56, v51
	v_rsq_f32_e32 v57, v52
	v_rsq_f32_e32 v58, v53
	v_rsq_f32_e32 v59, v54
	v_mul_f32_e32 v50, v50, v55
	v_mul_f32_e32 v51, v51, v56
	v_mul_f32_e32 v52, v52, v57
	v_mul_f32_e32 v53, v53, v58
	v_mul_f32_e32 v54, v54, v59
	v_fma_f32 v50, -v50, v55, 1.0
	v_fma_f32 v51, -v51, v56, 1.0
	v_fma_f32 v52, -v52, v57, 1.0
	v_fma_f32 v53, -v53, v58, 1.0
	v_fma_f32 v54, -v54, v59, 1.0
	v_mul_f32_e32 v50, 0.5, v50
	v_mul_f32_e32 v51, 0.5, v51
	v_mul_f32_e32 v52, 0.5, v52
	v_mul_f32_e32 v53, 0.5, v53
	v_mul_f32_e32 v54, 0.5, v54
	v_fmac_f32_e32 v55, v55, v50
	v_fmac_f32_e32 v56, v56, v51
	v_fmac_f32_e32 v57, v57, v52
	v_fmac_f32_e32 v58, v58, v53
	v_fmac_f32_e32 v59, v59, v54
	v_mov_b32_e32 v70, s40
	v_mov_b32_e32 v71, s41
	v_cndmask_b32_e64 v70, v71, v70, s[42:43]
	v_cvt_f32_ubyte0_e32 v70, v70
	v_mul_f32_e32 v60, v26, v70
	v_mul_f32_e32 v62, v27, v70
	v_mul_f32_e32 v61, 0.15915494, v60
	v_mul_f32_e32 v63, 0.15915494, v62
	v_rndne_f32_e32 v61, v61
	v_rndne_f32_e32 v63, v63
	v_fmac_f32_e32 v60, 0xc0c90fdb, v61
	v_fmac_f32_e32 v62, 0xc0c90fdb, v63
	v_fmac_f32_e32 v60, 0x343bbd2e, v61
	v_fmac_f32_e32 v62, 0x343bbd2e, v63
	v_mul_f32_e32 v60, 0.15915494, v60
	v_mul_f32_e32 v62, 0.15915494, v62
	v_sin_f32_e32 v61, v60
	v_sin_f32_e32 v63, v62
	v_cos_f32_e32 v60, v60
	v_cos_f32_e32 v62, v62
	v_mul_f32_e32 v30, v30, v55
	v_mul_f32_e32 v31, v31, v55
	v_mul_f32_e32 v32, v32, v55
	v_mul_f32_e32 v33, v33, v55
	v_mul_f32_e32 v30, v30, v4
	v_mul_f32_e32 v31, v31, v5
	v_mul_f32_e32 v32, v32, v6
	v_mul_f32_e32 v33, v33, v7
	v_mul_f32_e32 v64, v61, v32
	v_mul_f32_e32 v65, v63, v33
	v_mul_f32_e32 v66, v60, v32
	v_mul_f32_e32 v67, v62, v33
	v_fma_f32 v64, v60, v30, -v64
	v_fma_f32 v65, v62, v31, -v65
	v_fmac_f32_e32 v66, v61, v30
	v_fmac_f32_e32 v67, v63, v31
	v_cvt_pk_bf16_f32 v68, v64, v65
	v_cvt_pk_bf16_f32 v69, v66, v67
	global_store_dword v18, v68, s[74:75] offset:0
	global_store_dword v18, v69, s[74:75] offset:64
	v_mul_f32_e32 v34, v34, v56
	v_mul_f32_e32 v35, v35, v56
	v_mul_f32_e32 v36, v36, v56
	v_mul_f32_e32 v37, v37, v56
	v_mul_f32_e32 v34, v34, v4
	v_mul_f32_e32 v35, v35, v5
	v_mul_f32_e32 v36, v36, v6
	v_mul_f32_e32 v37, v37, v7
	v_mul_f32_e32 v64, v61, v36
	v_mul_f32_e32 v65, v63, v37
	v_mul_f32_e32 v66, v60, v36
	v_mul_f32_e32 v67, v62, v37
	v_fma_f32 v64, v60, v34, -v64
	v_fma_f32 v65, v62, v35, -v65
	v_fmac_f32_e32 v66, v61, v34
	v_fmac_f32_e32 v67, v63, v35
	v_cvt_pk_bf16_f32 v68, v64, v65
	v_cvt_pk_bf16_f32 v69, v66, v67
	global_store_dword v18, v68, s[74:75] offset:512
	global_store_dword v18, v69, s[74:75] offset:576
	v_mul_f32_e32 v38, v38, v57
	v_mul_f32_e32 v39, v39, v57
	v_mul_f32_e32 v40, v40, v57
	v_mul_f32_e32 v41, v41, v57
	v_mul_f32_e32 v38, v38, v4
	v_mul_f32_e32 v39, v39, v5
	v_mul_f32_e32 v40, v40, v6
	v_mul_f32_e32 v41, v41, v7
	v_mul_f32_e32 v64, v61, v40
	v_mul_f32_e32 v65, v63, v41
	v_mul_f32_e32 v66, v60, v40
	v_mul_f32_e32 v67, v62, v41
	v_fma_f32 v64, v60, v38, -v64
	v_fma_f32 v65, v62, v39, -v65
	v_fmac_f32_e32 v66, v61, v38
	v_fmac_f32_e32 v67, v63, v39
	v_cvt_pk_bf16_f32 v68, v64, v65
	v_cvt_pk_bf16_f32 v69, v66, v67
	global_store_dword v18, v68, s[74:75] offset:1024
	global_store_dword v18, v69, s[74:75] offset:1088
	v_mul_f32_e32 v42, v42, v58
	v_mul_f32_e32 v43, v43, v58
	v_mul_f32_e32 v44, v44, v58
	v_mul_f32_e32 v45, v45, v58
	v_mul_f32_e32 v42, v42, v4
	v_mul_f32_e32 v43, v43, v5
	v_mul_f32_e32 v44, v44, v6
	v_mul_f32_e32 v45, v45, v7
	v_mul_f32_e32 v64, v61, v44
	v_mul_f32_e32 v65, v63, v45
	v_mul_f32_e32 v66, v60, v44
	v_mul_f32_e32 v67, v62, v45
	v_fma_f32 v64, v60, v42, -v64
	v_fma_f32 v65, v62, v43, -v65
	v_fmac_f32_e32 v66, v61, v42
	v_fmac_f32_e32 v67, v63, v43
	v_cvt_pk_bf16_f32 v68, v64, v65
	v_cvt_pk_bf16_f32 v69, v66, v67
	global_store_dword v18, v68, s[74:75] offset:1536
	global_store_dword v18, v69, s[74:75] offset:1600
	v_mul_f32_e32 v46, v46, v59
	v_mul_f32_e32 v47, v47, v59
	v_mul_f32_e32 v48, v48, v59
	v_mul_f32_e32 v49, v49, v59
	v_mul_f32_e32 v46, v46, v8
	v_mul_f32_e32 v47, v47, v9
	v_mul_f32_e32 v48, v48, v10
	v_mul_f32_e32 v49, v49, v11
	v_mul_f32_e32 v64, v61, v48
	v_mul_f32_e32 v65, v63, v49
	v_mul_f32_e32 v66, v60, v48
	v_mul_f32_e32 v67, v62, v49
	v_fma_f32 v64, v60, v46, -v64
	v_fma_f32 v65, v62, v47, -v65
	v_fmac_f32_e32 v66, v61, v46
	v_fmac_f32_e32 v67, v63, v47
	v_cvt_pk_bf16_f32 v68, v64, v65
	v_cvt_pk_bf16_f32 v69, v66, v67
	global_store_dword v19, v68, s[76:77]
	global_store_dword v19, v69, s[76:77] offset:64
	s_add_i32 s71, s70, 0x2000
	s_bfe_u32 s40, s71, 0x60006
	s_and_b32 s41, s71, 63
	s_sub_i32 s10, s71, 0x1000
	s_lshr_b32 s11, s10, 12
	s_and_b32 s10, s10, 0xfff
	s_mulk_i32 s11, 0x2200
	s_add_i32 s10, s10, s11
	s_addk_i32 s10, 0x100
	s_lshl_b32 s74, s71, 11
	s_add_u32 s74, s74, 0x87c8000
	s_add_u32 s74, s54, s74
	s_addc_u32 s75, s55, 0
	s_lshl_b32 s76, s10, 8
	s_add_u32 s78, s76, 0x13208000
	s_add_u32 s76, s76, 0x12dc8000
	s_add_u32 s76, s54, s76
	s_addc_u32 s77, s55, 0
	s_add_u32 s78, s54, s78
	s_addc_u32 s79, s55, 0
	s_add_u32 s80, s78, 0x110000
	s_addc_u32 s81, s79, 0
	s_waitcnt vmcnt(63)
	global_store_dword v22, v158, s[78:79]
	global_store_dword v22, v159, s[80:81]
	v_lshlrev_b32_e32 v30, 16, v148
	v_and_b32_e32 v31, 0xffff0000, v148
	v_lshlrev_b32_e32 v32, 16, v149
	v_and_b32_e32 v33, 0xffff0000, v149
	v_lshlrev_b32_e32 v34, 16, v150
	v_and_b32_e32 v35, 0xffff0000, v150
	v_lshlrev_b32_e32 v36, 16, v151
	v_and_b32_e32 v37, 0xffff0000, v151
	v_lshlrev_b32_e32 v38, 16, v152
	v_and_b32_e32 v39, 0xffff0000, v152
	v_lshlrev_b32_e32 v40, 16, v153
	v_and_b32_e32 v41, 0xffff0000, v153
	v_lshlrev_b32_e32 v42, 16, v154
	v_and_b32_e32 v43, 0xffff0000, v154
	v_lshlrev_b32_e32 v44, 16, v155
	v_and_b32_e32 v45, 0xffff0000, v155
	v_lshlrev_b32_e32 v46, 16, v156
	v_and_b32_e32 v47, 0xffff0000, v156
	v_lshlrev_b32_e32 v48, 16, v157
	v_and_b32_e32 v49, 0xffff0000, v157
	v_mul_f32_e32 v50, v30, v30
	v_mul_f32_e32 v51, v34, v34
	v_mul_f32_e32 v52, v38, v38
	v_mul_f32_e32 v53, v42, v42
	v_mul_f32_e32 v54, v46, v46
	v_fmac_f32_e32 v50, v31, v31
	v_fmac_f32_e32 v51, v35, v35
	v_fmac_f32_e32 v52, v39, v39
	v_fmac_f32_e32 v53, v43, v43
	v_fmac_f32_e32 v54, v47, v47
	v_fmac_f32_e32 v50, v32, v32
	v_fmac_f32_e32 v51, v36, v36
	v_fmac_f32_e32 v52, v40, v40
	v_fmac_f32_e32 v53, v44, v44
	v_fmac_f32_e32 v54, v48, v48
	v_fmac_f32_e32 v50, v33, v33
	v_fmac_f32_e32 v51, v37, v37
	v_fmac_f32_e32 v52, v41, v41
	v_fmac_f32_e32 v53, v45, v45
	v_fmac_f32_e32 v54, v49, v49
	v_add_f32_dpp v50, v50, v50 quad_perm:[1,0,3,2] row_mask:0xf bank_mask:0xf
	v_add_f32_dpp v51, v51, v51 quad_perm:[1,0,3,2] row_mask:0xf bank_mask:0xf
	v_add_f32_dpp v52, v52, v52 quad_perm:[1,0,3,2] row_mask:0xf bank_mask:0xf
	v_add_f32_dpp v53, v53, v53 quad_perm:[1,0,3,2] row_mask:0xf bank_mask:0xf
	v_add_f32_dpp v54, v54, v54 quad_perm:[1,0,3,2] row_mask:0xf bank_mask:0xf
	v_add_f32_dpp v50, v50, v50 quad_perm:[2,3,0,1] row_mask:0xf bank_mask:0xf
	v_add_f32_dpp v51, v51, v51 quad_perm:[2,3,0,1] row_mask:0xf bank_mask:0xf
	v_add_f32_dpp v52, v52, v52 quad_perm:[2,3,0,1] row_mask:0xf bank_mask:0xf
	v_add_f32_dpp v53, v53, v53 quad_perm:[2,3,0,1] row_mask:0xf bank_mask:0xf
	v_add_f32_dpp v54, v54, v54 quad_perm:[2,3,0,1] row_mask:0xf bank_mask:0xf
	v_add_f32_dpp v50, v50, v50 row_half_mirror row_mask:0xf bank_mask:0xf
	v_add_f32_dpp v51, v51, v51 row_half_mirror row_mask:0xf bank_mask:0xf
	v_add_f32_dpp v52, v52, v52 row_half_mirror row_mask:0xf bank_mask:0xf
	v_add_f32_dpp v53, v53, v53 row_half_mirror row_mask:0xf bank_mask:0xf
	v_add_f32_dpp v54, v54, v54 row_half_mirror row_mask:0xf bank_mask:0xf
	v_add_f32_dpp v50, v50, v50 row_mirror row_mask:0xf bank_mask:0xf
	v_add_f32_dpp v51, v51, v51 row_mirror row_mask:0xf bank_mask:0xf
	v_add_f32_dpp v52, v52, v52 row_mirror row_mask:0xf bank_mask:0xf
	v_add_f32_dpp v53, v53, v53 row_mirror row_mask:0xf bank_mask:0xf
	v_add_f32_dpp v54, v54, v54 row_mirror row_mask:0xf bank_mask:0xf
	v_mov_b32_e32 v55, v50
	v_mov_b32_e32 v56, v51
	v_mov_b32_e32 v57, v52
	v_mov_b32_e32 v58, v53
	v_mov_b32_e32 v59, v54
	s_nop 1
	v_permlane16_swap_b32_e32 v50, v55
	v_permlane16_swap_b32_e32 v51, v56
	v_permlane16_swap_b32_e32 v52, v57
	v_permlane16_swap_b32_e32 v53, v58
	v_permlane16_swap_b32_e32 v54, v59
	v_add_f32_e32 v50, v50, v55
	v_add_f32_e32 v51, v51, v56
	v_add_f32_e32 v52, v52, v57
	v_add_f32_e32 v53, v53, v58
	v_add_f32_e32 v54, v54, v59
	v_fmamk_f32 v50, v50, 0x3c000000, v207
	v_fmamk_f32 v51, v51, 0x3c000000, v207
	v_fmamk_f32 v52, v52, 0x3c000000, v207
	v_fmamk_f32 v53, v53, 0x3c000000, v207
	v_fmamk_f32 v54, v54, 0x3c000000, v207
	v_rsq_f32_e32 v55, v50
	v_rsq_f32_e32 v56, v51
	v_rsq_f32_e32 v57, v52
	v_rsq_f32_e32 v58, v53
	v_rsq_f32_e32 v59, v54
	v_mul_f32_e32 v50, v50, v55
	v_mul_f32_e32 v51, v51, v56
	v_mul_f32_e32 v52, v52, v57
	v_mul_f32_e32 v53, v53, v58
	v_mul_f32_e32 v54, v54, v59
	v_fma_f32 v50, -v50, v55, 1.0
	v_fma_f32 v51, -v51, v56, 1.0
	v_fma_f32 v52, -v52, v57, 1.0
	v_fma_f32 v53, -v53, v58, 1.0
	v_fma_f32 v54, -v54, v59, 1.0
	v_mul_f32_e32 v50, 0.5, v50
	v_mul_f32_e32 v51, 0.5, v51
	v_mul_f32_e32 v52, 0.5, v52
	v_mul_f32_e32 v53, 0.5, v53
	v_mul_f32_e32 v54, 0.5, v54
	v_fmac_f32_e32 v55, v55, v50
	v_fmac_f32_e32 v56, v56, v51
	v_fmac_f32_e32 v57, v57, v52
	v_fmac_f32_e32 v58, v58, v53
	v_fmac_f32_e32 v59, v59, v54
	v_mov_b32_e32 v70, s40
	v_mov_b32_e32 v71, s41
	v_cndmask_b32_e64 v70, v71, v70, s[42:43]
	v_cvt_f32_ubyte0_e32 v70, v70
	v_mul_f32_e32 v60, v26, v70
	v_mul_f32_e32 v62, v27, v70
	v_mul_f32_e32 v61, 0.15915494, v60
	v_mul_f32_e32 v63, 0.15915494, v62
	v_rndne_f32_e32 v61, v61
	v_rndne_f32_e32 v63, v63
	v_fmac_f32_e32 v60, 0xc0c90fdb, v61
	v_fmac_f32_e32 v62, 0xc0c90fdb, v63
	v_fmac_f32_e32 v60, 0x343bbd2e, v61
	v_fmac_f32_e32 v62, 0x343bbd2e, v63
	v_mul_f32_e32 v60, 0.15915494, v60
	v_mul_f32_e32 v62, 0.15915494, v62
	v_sin_f32_e32 v61, v60
	v_sin_f32_e32 v63, v62
	v_cos_f32_e32 v60, v60
	v_cos_f32_e32 v62, v62
	v_mul_f32_e32 v30, v30, v55
	v_mul_f32_e32 v31, v31, v55
	v_mul_f32_e32 v32, v32, v55
	v_mul_f32_e32 v33, v33, v55
	v_mul_f32_e32 v30, v30, v4
	v_mul_f32_e32 v31, v31, v5
	v_mul_f32_e32 v32, v32, v6
	v_mul_f32_e32 v33, v33, v7
	v_mul_f32_e32 v64, v61, v32
	v_mul_f32_e32 v65, v63, v33
	v_mul_f32_e32 v66, v60, v32
	v_mul_f32_e32 v67, v62, v33
	v_fma_f32 v64, v60, v30, -v64
	v_fma_f32 v65, v62, v31, -v65
	v_fmac_f32_e32 v66, v61, v30
	v_fmac_f32_e32 v67, v63, v31
	v_cvt_pk_bf16_f32 v68, v64, v65
	v_cvt_pk_bf16_f32 v69, v66, v67
	global_store_dword v18, v68, s[74:75] offset:0
	global_store_dword v18, v69, s[74:75] offset:64
	v_mul_f32_e32 v34, v34, v56
	v_mul_f32_e32 v35, v35, v56
	v_mul_f32_e32 v36, v36, v56
	v_mul_f32_e32 v37, v37, v56
	v_mul_f32_e32 v34, v34, v4
	v_mul_f32_e32 v35, v35, v5
	v_mul_f32_e32 v36, v36, v6
	v_mul_f32_e32 v37, v37, v7
	v_mul_f32_e32 v64, v61, v36
	v_mul_f32_e32 v65, v63, v37
	v_mul_f32_e32 v66, v60, v36
	v_mul_f32_e32 v67, v62, v37
	v_fma_f32 v64, v60, v34, -v64
	v_fma_f32 v65, v62, v35, -v65
	v_fmac_f32_e32 v66, v61, v34
	v_fmac_f32_e32 v67, v63, v35
	v_cvt_pk_bf16_f32 v68, v64, v65
	v_cvt_pk_bf16_f32 v69, v66, v67
	global_store_dword v18, v68, s[74:75] offset:512
	global_store_dword v18, v69, s[74:75] offset:576
	v_mul_f32_e32 v38, v38, v57
	v_mul_f32_e32 v39, v39, v57
	v_mul_f32_e32 v40, v40, v57
	v_mul_f32_e32 v41, v41, v57
	v_mul_f32_e32 v38, v38, v4
	v_mul_f32_e32 v39, v39, v5
	v_mul_f32_e32 v40, v40, v6
	v_mul_f32_e32 v41, v41, v7
	v_mul_f32_e32 v64, v61, v40
	v_mul_f32_e32 v65, v63, v41
	v_mul_f32_e32 v66, v60, v40
	v_mul_f32_e32 v67, v62, v41
	v_fma_f32 v64, v60, v38, -v64
	v_fma_f32 v65, v62, v39, -v65
	v_fmac_f32_e32 v66, v61, v38
	v_fmac_f32_e32 v67, v63, v39
	v_cvt_pk_bf16_f32 v68, v64, v65
	v_cvt_pk_bf16_f32 v69, v66, v67
	global_store_dword v18, v68, s[74:75] offset:1024
	global_store_dword v18, v69, s[74:75] offset:1088
	v_mul_f32_e32 v42, v42, v58
	v_mul_f32_e32 v43, v43, v58
	v_mul_f32_e32 v44, v44, v58
	v_mul_f32_e32 v45, v45, v58
	v_mul_f32_e32 v42, v42, v4
	v_mul_f32_e32 v43, v43, v5
	v_mul_f32_e32 v44, v44, v6
	v_mul_f32_e32 v45, v45, v7
	v_mul_f32_e32 v64, v61, v44
	v_mul_f32_e32 v65, v63, v45
	v_mul_f32_e32 v66, v60, v44
	v_mul_f32_e32 v67, v62, v45
	v_fma_f32 v64, v60, v42, -v64
	v_fma_f32 v65, v62, v43, -v65
	v_fmac_f32_e32 v66, v61, v42
	v_fmac_f32_e32 v67, v63, v43
	v_cvt_pk_bf16_f32 v68, v64, v65
	v_cvt_pk_bf16_f32 v69, v66, v67
	global_store_dword v18, v68, s[74:75] offset:1536
	global_store_dword v18, v69, s[74:75] offset:1600
	v_mul_f32_e32 v46, v46, v59
	v_mul_f32_e32 v47, v47, v59
	v_mul_f32_e32 v48, v48, v59
	v_mul_f32_e32 v49, v49, v59
	v_mul_f32_e32 v46, v46, v8
	v_mul_f32_e32 v47, v47, v9
	v_mul_f32_e32 v48, v48, v10
	v_mul_f32_e32 v49, v49, v11
	v_mul_f32_e32 v64, v61, v48
	v_mul_f32_e32 v65, v63, v49
	v_mul_f32_e32 v66, v60, v48
	v_mul_f32_e32 v67, v62, v49
	v_fma_f32 v64, v60, v46, -v64
	v_fma_f32 v65, v62, v47, -v65
	v_fmac_f32_e32 v66, v61, v46
	v_fmac_f32_e32 v67, v63, v47
	v_cvt_pk_bf16_f32 v68, v64, v65
	v_cvt_pk_bf16_f32 v69, v66, v67
	global_store_dword v19, v68, s[76:77]
	global_store_dword v19, v69, s[76:77] offset:64
	s_add_i32 s71, s70, 0x2800
	s_bfe_u32 s40, s71, 0x60006
	s_and_b32 s41, s71, 63
	s_sub_i32 s10, s71, 0x1000
	s_lshr_b32 s11, s10, 12
	s_and_b32 s10, s10, 0xfff
	s_mulk_i32 s11, 0x2200
	s_add_i32 s10, s10, s11
	s_addk_i32 s10, 0x100
	s_lshl_b32 s74, s71, 11
	s_add_u32 s74, s74, 0x87c8000
	s_add_u32 s74, s54, s74
	s_addc_u32 s75, s55, 0
	s_lshl_b32 s76, s10, 8
	s_add_u32 s78, s76, 0x13208000
	s_add_u32 s76, s76, 0x12dc8000
	s_add_u32 s76, s54, s76
	s_addc_u32 s77, s55, 0
	s_add_u32 s78, s54, s78
	s_addc_u32 s79, s55, 0
	s_add_u32 s80, s78, 0x110000
	s_addc_u32 s81, s79, 0
	s_waitcnt vmcnt(63)
	global_store_dword v22, v170, s[78:79]
	global_store_dword v22, v171, s[80:81]
	v_lshlrev_b32_e32 v30, 16, v160
	v_and_b32_e32 v31, 0xffff0000, v160
	v_lshlrev_b32_e32 v32, 16, v161
	v_and_b32_e32 v33, 0xffff0000, v161
	v_lshlrev_b32_e32 v34, 16, v162
	v_and_b32_e32 v35, 0xffff0000, v162
	v_lshlrev_b32_e32 v36, 16, v163
	v_and_b32_e32 v37, 0xffff0000, v163
	v_lshlrev_b32_e32 v38, 16, v164
	v_and_b32_e32 v39, 0xffff0000, v164
	v_lshlrev_b32_e32 v40, 16, v165
	v_and_b32_e32 v41, 0xffff0000, v165
	v_lshlrev_b32_e32 v42, 16, v166
	v_and_b32_e32 v43, 0xffff0000, v166
	v_lshlrev_b32_e32 v44, 16, v167
	v_and_b32_e32 v45, 0xffff0000, v167
	v_lshlrev_b32_e32 v46, 16, v168
	v_and_b32_e32 v47, 0xffff0000, v168
	v_lshlrev_b32_e32 v48, 16, v169
	v_and_b32_e32 v49, 0xffff0000, v169
	v_mul_f32_e32 v50, v30, v30
	v_mul_f32_e32 v51, v34, v34
	v_mul_f32_e32 v52, v38, v38
	v_mul_f32_e32 v53, v42, v42
	v_mul_f32_e32 v54, v46, v46
	v_fmac_f32_e32 v50, v31, v31
	v_fmac_f32_e32 v51, v35, v35
	v_fmac_f32_e32 v52, v39, v39
	v_fmac_f32_e32 v53, v43, v43
	v_fmac_f32_e32 v54, v47, v47
	v_fmac_f32_e32 v50, v32, v32
	v_fmac_f32_e32 v51, v36, v36
	v_fmac_f32_e32 v52, v40, v40
	v_fmac_f32_e32 v53, v44, v44
	v_fmac_f32_e32 v54, v48, v48
	v_fmac_f32_e32 v50, v33, v33
	v_fmac_f32_e32 v51, v37, v37
	v_fmac_f32_e32 v52, v41, v41
	v_fmac_f32_e32 v53, v45, v45
	v_fmac_f32_e32 v54, v49, v49
	v_add_f32_dpp v50, v50, v50 quad_perm:[1,0,3,2] row_mask:0xf bank_mask:0xf
	v_add_f32_dpp v51, v51, v51 quad_perm:[1,0,3,2] row_mask:0xf bank_mask:0xf
	v_add_f32_dpp v52, v52, v52 quad_perm:[1,0,3,2] row_mask:0xf bank_mask:0xf
	v_add_f32_dpp v53, v53, v53 quad_perm:[1,0,3,2] row_mask:0xf bank_mask:0xf
	v_add_f32_dpp v54, v54, v54 quad_perm:[1,0,3,2] row_mask:0xf bank_mask:0xf
	v_add_f32_dpp v50, v50, v50 quad_perm:[2,3,0,1] row_mask:0xf bank_mask:0xf
	v_add_f32_dpp v51, v51, v51 quad_perm:[2,3,0,1] row_mask:0xf bank_mask:0xf
	v_add_f32_dpp v52, v52, v52 quad_perm:[2,3,0,1] row_mask:0xf bank_mask:0xf
	v_add_f32_dpp v53, v53, v53 quad_perm:[2,3,0,1] row_mask:0xf bank_mask:0xf
	v_add_f32_dpp v54, v54, v54 quad_perm:[2,3,0,1] row_mask:0xf bank_mask:0xf
	v_add_f32_dpp v50, v50, v50 row_half_mirror row_mask:0xf bank_mask:0xf
	v_add_f32_dpp v51, v51, v51 row_half_mirror row_mask:0xf bank_mask:0xf
	v_add_f32_dpp v52, v52, v52 row_half_mirror row_mask:0xf bank_mask:0xf
	v_add_f32_dpp v53, v53, v53 row_half_mirror row_mask:0xf bank_mask:0xf
	v_add_f32_dpp v54, v54, v54 row_half_mirror row_mask:0xf bank_mask:0xf
	v_add_f32_dpp v50, v50, v50 row_mirror row_mask:0xf bank_mask:0xf
	v_add_f32_dpp v51, v51, v51 row_mirror row_mask:0xf bank_mask:0xf
	v_add_f32_dpp v52, v52, v52 row_mirror row_mask:0xf bank_mask:0xf
	v_add_f32_dpp v53, v53, v53 row_mirror row_mask:0xf bank_mask:0xf
	v_add_f32_dpp v54, v54, v54 row_mirror row_mask:0xf bank_mask:0xf
	v_mov_b32_e32 v55, v50
	v_mov_b32_e32 v56, v51
	v_mov_b32_e32 v57, v52
	v_mov_b32_e32 v58, v53
	v_mov_b32_e32 v59, v54
	s_nop 1
	v_permlane16_swap_b32_e32 v50, v55
	v_permlane16_swap_b32_e32 v51, v56
	v_permlane16_swap_b32_e32 v52, v57
	v_permlane16_swap_b32_e32 v53, v58
	v_permlane16_swap_b32_e32 v54, v59
	v_add_f32_e32 v50, v50, v55
	v_add_f32_e32 v51, v51, v56
	v_add_f32_e32 v52, v52, v57
	v_add_f32_e32 v53, v53, v58
	v_add_f32_e32 v54, v54, v59
	v_fmamk_f32 v50, v50, 0x3c000000, v207
	v_fmamk_f32 v51, v51, 0x3c000000, v207
	v_fmamk_f32 v52, v52, 0x3c000000, v207
	v_fmamk_f32 v53, v53, 0x3c000000, v207
	v_fmamk_f32 v54, v54, 0x3c000000, v207
	v_rsq_f32_e32 v55, v50
	v_rsq_f32_e32 v56, v51
	v_rsq_f32_e32 v57, v52
	v_rsq_f32_e32 v58, v53
	v_rsq_f32_e32 v59, v54
	v_mul_f32_e32 v50, v50, v55
	v_mul_f32_e32 v51, v51, v56
	v_mul_f32_e32 v52, v52, v57
	v_mul_f32_e32 v53, v53, v58
	v_mul_f32_e32 v54, v54, v59
	v_fma_f32 v50, -v50, v55, 1.0
	v_fma_f32 v51, -v51, v56, 1.0
	v_fma_f32 v52, -v52, v57, 1.0
	v_fma_f32 v53, -v53, v58, 1.0
	v_fma_f32 v54, -v54, v59, 1.0
	v_mul_f32_e32 v50, 0.5, v50
	v_mul_f32_e32 v51, 0.5, v51
	v_mul_f32_e32 v52, 0.5, v52
	v_mul_f32_e32 v53, 0.5, v53
	v_mul_f32_e32 v54, 0.5, v54
	v_fmac_f32_e32 v55, v55, v50
	v_fmac_f32_e32 v56, v56, v51
	v_fmac_f32_e32 v57, v57, v52
	v_fmac_f32_e32 v58, v58, v53
	v_fmac_f32_e32 v59, v59, v54
	v_mov_b32_e32 v70, s40
	v_mov_b32_e32 v71, s41
	v_cndmask_b32_e64 v70, v71, v70, s[42:43]
	v_cvt_f32_ubyte0_e32 v70, v70
	v_mul_f32_e32 v60, v26, v70
	v_mul_f32_e32 v62, v27, v70
	v_mul_f32_e32 v61, 0.15915494, v60
	v_mul_f32_e32 v63, 0.15915494, v62
	v_rndne_f32_e32 v61, v61
	v_rndne_f32_e32 v63, v63
	v_fmac_f32_e32 v60, 0xc0c90fdb, v61
	v_fmac_f32_e32 v62, 0xc0c90fdb, v63
	v_fmac_f32_e32 v60, 0x343bbd2e, v61
	v_fmac_f32_e32 v62, 0x343bbd2e, v63
	v_mul_f32_e32 v60, 0.15915494, v60
	v_mul_f32_e32 v62, 0.15915494, v62
	v_sin_f32_e32 v61, v60
	v_sin_f32_e32 v63, v62
	v_cos_f32_e32 v60, v60
	v_cos_f32_e32 v62, v62
	v_mul_f32_e32 v30, v30, v55
	v_mul_f32_e32 v31, v31, v55
	v_mul_f32_e32 v32, v32, v55
	v_mul_f32_e32 v33, v33, v55
	v_mul_f32_e32 v30, v30, v4
	v_mul_f32_e32 v31, v31, v5
	v_mul_f32_e32 v32, v32, v6
	v_mul_f32_e32 v33, v33, v7
	v_mul_f32_e32 v64, v61, v32
	v_mul_f32_e32 v65, v63, v33
	v_mul_f32_e32 v66, v60, v32
	v_mul_f32_e32 v67, v62, v33
	v_fma_f32 v64, v60, v30, -v64
	v_fma_f32 v65, v62, v31, -v65
	v_fmac_f32_e32 v66, v61, v30
	v_fmac_f32_e32 v67, v63, v31
	v_cvt_pk_bf16_f32 v68, v64, v65
	v_cvt_pk_bf16_f32 v69, v66, v67
	global_store_dword v18, v68, s[74:75] offset:0
	global_store_dword v18, v69, s[74:75] offset:64
	v_mul_f32_e32 v34, v34, v56
	v_mul_f32_e32 v35, v35, v56
	v_mul_f32_e32 v36, v36, v56
	v_mul_f32_e32 v37, v37, v56
	v_mul_f32_e32 v34, v34, v4
	v_mul_f32_e32 v35, v35, v5
	v_mul_f32_e32 v36, v36, v6
	v_mul_f32_e32 v37, v37, v7
	v_mul_f32_e32 v64, v61, v36
	v_mul_f32_e32 v65, v63, v37
	v_mul_f32_e32 v66, v60, v36
	v_mul_f32_e32 v67, v62, v37
	v_fma_f32 v64, v60, v34, -v64
	v_fma_f32 v65, v62, v35, -v65
	v_fmac_f32_e32 v66, v61, v34
	v_fmac_f32_e32 v67, v63, v35
	v_cvt_pk_bf16_f32 v68, v64, v65
	v_cvt_pk_bf16_f32 v69, v66, v67
	global_store_dword v18, v68, s[74:75] offset:512
	global_store_dword v18, v69, s[74:75] offset:576
	v_mul_f32_e32 v38, v38, v57
	v_mul_f32_e32 v39, v39, v57
	v_mul_f32_e32 v40, v40, v57
	v_mul_f32_e32 v41, v41, v57
	v_mul_f32_e32 v38, v38, v4
	v_mul_f32_e32 v39, v39, v5
	v_mul_f32_e32 v40, v40, v6
	v_mul_f32_e32 v41, v41, v7
	v_mul_f32_e32 v64, v61, v40
	v_mul_f32_e32 v65, v63, v41
	v_mul_f32_e32 v66, v60, v40
	v_mul_f32_e32 v67, v62, v41
	v_fma_f32 v64, v60, v38, -v64
	v_fma_f32 v65, v62, v39, -v65
	v_fmac_f32_e32 v66, v61, v38
	v_fmac_f32_e32 v67, v63, v39
	v_cvt_pk_bf16_f32 v68, v64, v65
	v_cvt_pk_bf16_f32 v69, v66, v67
	global_store_dword v18, v68, s[74:75] offset:1024
	global_store_dword v18, v69, s[74:75] offset:1088
	v_mul_f32_e32 v42, v42, v58
	v_mul_f32_e32 v43, v43, v58
	v_mul_f32_e32 v44, v44, v58
	v_mul_f32_e32 v45, v45, v58
	v_mul_f32_e32 v42, v42, v4
	v_mul_f32_e32 v43, v43, v5
	v_mul_f32_e32 v44, v44, v6
	v_mul_f32_e32 v45, v45, v7
	v_mul_f32_e32 v64, v61, v44
	v_mul_f32_e32 v65, v63, v45
	v_mul_f32_e32 v66, v60, v44
	v_mul_f32_e32 v67, v62, v45
	v_fma_f32 v64, v60, v42, -v64
	v_fma_f32 v65, v62, v43, -v65
	v_fmac_f32_e32 v66, v61, v42
	v_fmac_f32_e32 v67, v63, v43
	v_cvt_pk_bf16_f32 v68, v64, v65
	v_cvt_pk_bf16_f32 v69, v66, v67
	global_store_dword v18, v68, s[74:75] offset:1536
	global_store_dword v18, v69, s[74:75] offset:1600
	v_mul_f32_e32 v46, v46, v59
	v_mul_f32_e32 v47, v47, v59
	v_mul_f32_e32 v48, v48, v59
	v_mul_f32_e32 v49, v49, v59
	v_mul_f32_e32 v46, v46, v8
	v_mul_f32_e32 v47, v47, v9
	v_mul_f32_e32 v48, v48, v10
	v_mul_f32_e32 v49, v49, v11
	v_mul_f32_e32 v64, v61, v48
	v_mul_f32_e32 v65, v63, v49
	v_mul_f32_e32 v66, v60, v48
	v_mul_f32_e32 v67, v62, v49
	v_fma_f32 v64, v60, v46, -v64
	v_fma_f32 v65, v62, v47, -v65
	v_fmac_f32_e32 v66, v61, v46
	v_fmac_f32_e32 v67, v63, v47
	v_cvt_pk_bf16_f32 v68, v64, v65
	v_cvt_pk_bf16_f32 v69, v66, v67
	global_store_dword v19, v68, s[76:77]
	global_store_dword v19, v69, s[76:77] offset:64
